# v36 plus X3 epilogue with DPP quad-perm instead of ds_bpermute and batched l reads, X3 segment prefix (cseg) reused across items of the same head
# baseline (speedup 1.0000x reference)
; __device__ __forceinline__ float bf2f(unsigned short b) { return __uint_as_float(((unsigned)b) << 16); }
; __device__ __forceinline__ int crow(int r, int hi) { return (r & 3) + 8 * (r >> 2) + 4 * hi; }
; __device__ __forceinline__ void phase_x3(const Args& a, unsigned char* ldsg, int G) {
;     ...
;         if (hi == 0) li_l[r32] = l_reg; asm volatile("s_waitcnt lgkmcnt(0)" ::: "memory");
; #pragma unroll
;         for (int r = 0; r < 16; ++r) { const int orow = crow(r, hi); const float rli = __builtin_amdgcn_rcpf(li_l[orow]); const int grow = R0 + wid * QBLK + orow; const size_t off = (size_t)grow * DM + hb;
; #pragma unroll
;             for (int d0 = 0; d0 < 4; ++d0) { float v = o[d0][r] * rli * bf2f(GBp[off + d0 * 32 + r32]); if (grow < ROW_META) v = 0.f;
.LBB0_2260:
	s_and_saveexec_b64 s[22:23], s[6:7]
	ds_write_b32 v191, v220
	s_or_b64 exec, exec, s[22:23]
	v_or_b32_e32 v96, s0, v188
	v_ashrrev_i32_e32 v97, 31, v96
	v_lshlrev_b64 v[98:99], 11, v[96:97]
	v_lshl_add_u64 v[98:99], v[98:99], 0, s[40:41]
	v_lshlrev_b64 v[98:99], 1, v[98:99]
	v_lshl_add_u64 v[98:99], v[164:165], 0, v[98:99]
	global_load_ushort v0, v[98:99], off
	global_load_ushort v1, v[98:99], off offset:64
	global_load_ushort v2, v[98:99], off offset:128
	global_load_ushort v3, v[98:99], off offset:192
	v_or_b32_e32 v96, 1, v188
	v_or_b32_e32 v96, s0, v96
	v_ashrrev_i32_e32 v97, 31, v96
	v_lshlrev_b64 v[98:99], 11, v[96:97]
	v_lshl_add_u64 v[98:99], v[98:99], 0, s[40:41]
	v_lshlrev_b64 v[98:99], 1, v[98:99]
	v_lshl_add_u64 v[98:99], v[164:165], 0, v[98:99]
	global_load_ushort v4, v[98:99], off
	global_load_ushort v5, v[98:99], off offset:64
	global_load_ushort v6, v[98:99], off offset:128
	global_load_ushort v7, v[98:99], off offset:192
	v_or_b32_e32 v96, 2, v188
	v_or_b32_e32 v96, s0, v96
	v_ashrrev_i32_e32 v97, 31, v96
	v_lshlrev_b64 v[98:99], 11, v[96:97]
	v_lshl_add_u64 v[98:99], v[98:99], 0, s[40:41]
	v_lshlrev_b64 v[98:99], 1, v[98:99]
	v_lshl_add_u64 v[98:99], v[164:165], 0, v[98:99]
	global_load_ushort v8, v[98:99], off
	global_load_ushort v9, v[98:99], off offset:64
	global_load_ushort v10, v[98:99], off offset:128
	global_load_ushort v11, v[98:99], off offset:192
	v_or_b32_e32 v96, 3, v188
	v_or_b32_e32 v96, s0, v96
	v_ashrrev_i32_e32 v97, 31, v96
	v_lshlrev_b64 v[98:99], 11, v[96:97]
	v_lshl_add_u64 v[98:99], v[98:99], 0, s[40:41]
	v_lshlrev_b64 v[98:99], 1, v[98:99]
	v_lshl_add_u64 v[98:99], v[164:165], 0, v[98:99]
	global_load_ushort v12, v[98:99], off
	global_load_ushort v13, v[98:99], off offset:64
	global_load_ushort v14, v[98:99], off offset:128
	global_load_ushort v15, v[98:99], off offset:192
	v_or_b32_e32 v96, 8, v188
	v_or_b32_e32 v96, s0, v96
	v_ashrrev_i32_e32 v97, 31, v96
	v_lshlrev_b64 v[98:99], 11, v[96:97]
	v_lshl_add_u64 v[98:99], v[98:99], 0, s[40:41]
	v_lshlrev_b64 v[98:99], 1, v[98:99]
	v_lshl_add_u64 v[98:99], v[164:165], 0, v[98:99]
	global_load_ushort v16, v[98:99], off
	global_load_ushort v17, v[98:99], off offset:64
	global_load_ushort v18, v[98:99], off offset:128
	global_load_ushort v19, v[98:99], off offset:192
	v_or_b32_e32 v96, 9, v188
	v_or_b32_e32 v96, s0, v96
	v_ashrrev_i32_e32 v97, 31, v96
	v_lshlrev_b64 v[98:99], 11, v[96:97]
	v_lshl_add_u64 v[98:99], v[98:99], 0, s[40:41]
	v_lshlrev_b64 v[98:99], 1, v[98:99]
	v_lshl_add_u64 v[98:99], v[164:165], 0, v[98:99]
	global_load_ushort v20, v[98:99], off
	global_load_ushort v21, v[98:99], off offset:64
	global_load_ushort v22, v[98:99], off offset:128
	global_load_ushort v23, v[98:99], off offset:192
	v_or_b32_e32 v96, 10, v188
	v_or_b32_e32 v96, s0, v96
	v_ashrrev_i32_e32 v97, 31, v96
	v_lshlrev_b64 v[98:99], 11, v[96:97]
	v_lshl_add_u64 v[98:99], v[98:99], 0, s[40:41]
	v_lshlrev_b64 v[98:99], 1, v[98:99]
	v_lshl_add_u64 v[98:99], v[164:165], 0, v[98:99]
	global_load_ushort v24, v[98:99], off
	global_load_ushort v25, v[98:99], off offset:64
	global_load_ushort v26, v[98:99], off offset:128
	global_load_ushort v27, v[98:99], off offset:192
	v_or_b32_e32 v96, 11, v188
	v_or_b32_e32 v96, s0, v96
	v_ashrrev_i32_e32 v97, 31, v96
	v_lshlrev_b64 v[98:99], 11, v[96:97]
	v_lshl_add_u64 v[98:99], v[98:99], 0, s[40:41]
	v_lshlrev_b64 v[98:99], 1, v[98:99]
	v_lshl_add_u64 v[98:99], v[164:165], 0, v[98:99]
	global_load_ushort v28, v[98:99], off
	global_load_ushort v29, v[98:99], off offset:64
	global_load_ushort v30, v[98:99], off offset:128
	global_load_ushort v31, v[98:99], off offset:192
	v_or_b32_e32 v96, 16, v188
	v_or_b32_e32 v96, s0, v96
	v_ashrrev_i32_e32 v97, 31, v96
	v_lshlrev_b64 v[98:99], 11, v[96:97]
	v_lshl_add_u64 v[98:99], v[98:99], 0, s[40:41]
	v_lshlrev_b64 v[98:99], 1, v[98:99]
	v_lshl_add_u64 v[98:99], v[164:165], 0, v[98:99]
	global_load_ushort v106, v[98:99], off
	global_load_ushort v107, v[98:99], off offset:64
	global_load_ushort v108, v[98:99], off offset:128
	global_load_ushort v109, v[98:99], off offset:192
	v_or_b32_e32 v96, 17, v188
	v_or_b32_e32 v96, s0, v96
	v_ashrrev_i32_e32 v97, 31, v96
	v_lshlrev_b64 v[98:99], 11, v[96:97]
	v_lshl_add_u64 v[98:99], v[98:99], 0, s[40:41]
	v_lshlrev_b64 v[98:99], 1, v[98:99]
	v_lshl_add_u64 v[98:99], v[164:165], 0, v[98:99]
	global_load_ushort v110, v[98:99], off
	global_load_ushort v111, v[98:99], off offset:64
	global_load_ushort v112, v[98:99], off offset:128
	global_load_ushort v113, v[98:99], off offset:192
	v_or_b32_e32 v96, 18, v188
	v_or_b32_e32 v96, s0, v96
	v_ashrrev_i32_e32 v97, 31, v96
	v_lshlrev_b64 v[98:99], 11, v[96:97]
	v_lshl_add_u64 v[98:99], v[98:99], 0, s[40:41]
	v_lshlrev_b64 v[98:99], 1, v[98:99]
	v_lshl_add_u64 v[98:99], v[164:165], 0, v[98:99]
	global_load_ushort v114, v[98:99], off
	global_load_ushort v115, v[98:99], off offset:64
	global_load_ushort v116, v[98:99], off offset:128
	global_load_ushort v117, v[98:99], off offset:192
	v_or_b32_e32 v96, 19, v188
	v_or_b32_e32 v96, s0, v96
	v_ashrrev_i32_e32 v97, 31, v96
	v_lshlrev_b64 v[98:99], 11, v[96:97]
	v_lshl_add_u64 v[98:99], v[98:99], 0, s[40:41]
	v_lshlrev_b64 v[98:99], 1, v[98:99]
	v_lshl_add_u64 v[98:99], v[164:165], 0, v[98:99]
	global_load_ushort v118, v[98:99], off
	global_load_ushort v119, v[98:99], off offset:64
	global_load_ushort v120, v[98:99], off offset:128
	global_load_ushort v121, v[98:99], off offset:192
	v_or_b32_e32 v96, 24, v188
	v_or_b32_e32 v96, s0, v96
	v_ashrrev_i32_e32 v97, 31, v96
	v_lshlrev_b64 v[98:99], 11, v[96:97]
	v_lshl_add_u64 v[98:99], v[98:99], 0, s[40:41]
; __device__ __forceinline__ float bf2f(unsigned short b) { return __uint_as_float(((unsigned)b) << 16); }
; __device__ __forceinline__ int crow(int r, int hi) { return (r & 3) + 8 * (r >> 2) + 4 * hi; }
; __device__ __forceinline__ void phase_x3(const Args& a, unsigned char* ldsg, int G) {
;     ...
;         if (hi == 0) li_l[r32] = l_reg; asm volatile("s_waitcnt lgkmcnt(0)" ::: "memory");
; #pragma unroll
;         for (int r = 0; r < 16; ++r) { const int orow = crow(r, hi); const float rli = __builtin_amdgcn_rcpf(li_l[orow]); const int grow = R0 + wid * QBLK + orow; const size_t off = (size_t)grow * DM + hb;
; #pragma unroll
;             for (int d0 = 0; d0 < 4; ++d0) { float v = o[d0][r] * rli * bf2f(GBp[off + d0 * 32 + r32]); if (grow < ROW_META) v = 0.f;
;                 const float vn = __shfl_xor(v, 1);
;                 if ((r32 & 1) == 0) *(unsigned*)(OG + off + d0 * 32 + r32) = cvtpk(v, vn); } }
	v_lshlrev_b64 v[98:99], 1, v[98:99]
	v_lshl_add_u64 v[98:99], v[164:165], 0, v[98:99]
	global_load_ushort v122, v[98:99], off
	global_load_ushort v123, v[98:99], off offset:64
	global_load_ushort v124, v[98:99], off offset:128
	global_load_ushort v125, v[98:99], off offset:192
	v_or_b32_e32 v96, 25, v188
	v_or_b32_e32 v96, s0, v96
	v_ashrrev_i32_e32 v97, 31, v96
	v_lshlrev_b64 v[98:99], 11, v[96:97]
	v_lshl_add_u64 v[98:99], v[98:99], 0, s[40:41]
	v_lshlrev_b64 v[98:99], 1, v[98:99]
	v_lshl_add_u64 v[98:99], v[164:165], 0, v[98:99]
	global_load_ushort v126, v[98:99], off
	global_load_ushort v127, v[98:99], off offset:64
	global_load_ushort v128, v[98:99], off offset:128
	global_load_ushort v129, v[98:99], off offset:192
	v_or_b32_e32 v96, 26, v188
	v_or_b32_e32 v96, s0, v96
	v_ashrrev_i32_e32 v97, 31, v96
	v_lshlrev_b64 v[98:99], 11, v[96:97]
	v_lshl_add_u64 v[98:99], v[98:99], 0, s[40:41]
	v_lshlrev_b64 v[98:99], 1, v[98:99]
	v_lshl_add_u64 v[98:99], v[164:165], 0, v[98:99]
	global_load_ushort v130, v[98:99], off
	global_load_ushort v131, v[98:99], off offset:64
	global_load_ushort v132, v[98:99], off offset:128
	global_load_ushort v133, v[98:99], off offset:192
	v_or_b32_e32 v96, 27, v188
	v_or_b32_e32 v96, s0, v96
	v_ashrrev_i32_e32 v97, 31, v96
	v_lshlrev_b64 v[98:99], 11, v[96:97]
	v_lshl_add_u64 v[98:99], v[98:99], 0, s[40:41]
	v_lshlrev_b64 v[98:99], 1, v[98:99]
	v_lshl_add_u64 v[98:99], v[164:165], 0, v[98:99]
	global_load_ushort v134, v[98:99], off
	global_load_ushort v135, v[98:99], off offset:64
	global_load_ushort v136, v[98:99], off offset:128
	global_load_ushort v137, v[98:99], off offset:192
	v_and_b32_e32 v101, 64, v206
	v_add_u32_e32 v103, 64, v101
	v_xor_b32_e32 v102, 1, v206
	v_cmp_lt_i32_e32 vcc, v102, v103
	s_nop 1
	v_cndmask_b32_e32 v100, v206, v102, vcc
	v_lshlrev_b32_e32 v100, 2, v100
	s_waitcnt lgkmcnt(0)
	ds_read_b32 v138, v200
	ds_read_b32 v139, v200 offset:4
	ds_read_b32 v140, v200 offset:8
	ds_read_b32 v141, v200 offset:12
	ds_read_b32 v142, v200 offset:32
	ds_read_b32 v143, v200 offset:36
	ds_read_b32 v144, v200 offset:40
	ds_read_b32 v145, v200 offset:44
	ds_read_b32 v146, v200 offset:64
	ds_read_b32 v147, v200 offset:68
	ds_read_b32 v148, v200 offset:72
	ds_read_b32 v149, v200 offset:76
	ds_read_b32 v150, v200 offset:96
	ds_read_b32 v151, v200 offset:100
	ds_read_b32 v152, v200 offset:104
	ds_read_b32 v153, v200 offset:108
	s_waitcnt vmcnt(0) lgkmcnt(0)
	v_rcp_f32_e32 v138, v138
	v_rcp_f32_e32 v139, v139
	v_rcp_f32_e32 v140, v140
	v_rcp_f32_e32 v141, v141
	v_rcp_f32_e32 v142, v142
	v_rcp_f32_e32 v143, v143
	v_rcp_f32_e32 v144, v144
	v_rcp_f32_e32 v145, v145
	v_rcp_f32_e32 v146, v146
	v_rcp_f32_e32 v147, v147
	v_rcp_f32_e32 v148, v148
	v_rcp_f32_e32 v149, v149
	v_rcp_f32_e32 v150, v150
	v_rcp_f32_e32 v151, v151
	v_rcp_f32_e32 v152, v152
	v_rcp_f32_e32 v153, v153
	v_or_b32_e32 v96, s0, v188
	v_ashrrev_i32_e32 v97, 31, v96
	v_lshlrev_b64 v[98:99], 11, v[96:97]
	v_lshl_add_u64 v[98:99], v[98:99], 0, s[40:41]
	v_lshlrev_b64 v[98:99], 1, v[98:99]
	v_lshl_add_u64 v[98:99], v[166:167], 0, v[98:99]
	v_lshlrev_b32_e32 v0, 16, v0
	v_lshlrev_b32_e32 v1, 16, v1
	v_lshlrev_b32_e32 v2, 16, v2
	v_lshlrev_b32_e32 v3, 16, v3
	v_cmp_gt_i32_e32 vcc, s64, v96
	s_nop 0
	v_mul_f32_e32 v80, v80, v138
	v_mul_f32_e32 v64, v64, v138
	v_mul_f32_e32 v48, v48, v138
	v_mul_f32_e32 v32, v32, v138
	v_mul_f32_e32 v80, v80, v0
	v_mul_f32_e32 v64, v64, v1
	v_mul_f32_e32 v48, v48, v2
	v_mul_f32_e32 v32, v32, v3
	v_cndmask_b32_e64 v80, v80, 0, vcc
	v_cndmask_b32_e64 v64, v64, 0, vcc
	v_cndmask_b32_e64 v48, v48, 0, vcc
	v_cndmask_b32_e64 v32, v32, 0, vcc
	v_mov_b32_dpp v102, v80 quad_perm:[1,0,3,2] row_mask:0xf bank_mask:0xf
	v_mov_b32_dpp v103, v64 quad_perm:[1,0,3,2] row_mask:0xf bank_mask:0xf
	v_mov_b32_dpp v104, v48 quad_perm:[1,0,3,2] row_mask:0xf bank_mask:0xf
	v_mov_b32_dpp v105, v32 quad_perm:[1,0,3,2] row_mask:0xf bank_mask:0xf
	s_and_saveexec_b64 s[22:23], s[8:9]
	v_cvt_pk_bf16_f32 v80, v80, v102
	v_cvt_pk_bf16_f32 v64, v64, v103
	v_cvt_pk_bf16_f32 v48, v48, v104
	v_cvt_pk_bf16_f32 v32, v32, v105
	global_store_dword v[98:99], v80, off
	global_store_dword v[98:99], v64, off offset:64
	global_store_dword v[98:99], v48, off offset:128
	global_store_dword v[98:99], v32, off offset:192
	s_or_b64 exec, exec, s[22:23]
	v_or_b32_e32 v96, 1, v188
	v_or_b32_e32 v96, s0, v96
	v_ashrrev_i32_e32 v97, 31, v96
	v_lshlrev_b64 v[98:99], 11, v[96:97]
	v_lshl_add_u64 v[98:99], v[98:99], 0, s[40:41]
	v_lshlrev_b64 v[98:99], 1, v[98:99]
	v_lshl_add_u64 v[98:99], v[166:167], 0, v[98:99]
	v_lshlrev_b32_e32 v4, 16, v4
	v_lshlrev_b32_e32 v5, 16, v5
	v_lshlrev_b32_e32 v6, 16, v6
	v_lshlrev_b32_e32 v7, 16, v7
	v_cmp_gt_i32_e32 vcc, s64, v96
	s_nop 0
	v_mul_f32_e32 v81, v81, v139
	v_mul_f32_e32 v65, v65, v139
	v_mul_f32_e32 v49, v49, v139
	v_mul_f32_e32 v33, v33, v139
	v_mul_f32_e32 v81, v81, v4
	v_mul_f32_e32 v65, v65, v5
	v_mul_f32_e32 v49, v49, v6
	v_mul_f32_e32 v33, v33, v7
	v_cndmask_b32_e64 v81, v81, 0, vcc
	v_cndmask_b32_e64 v65, v65, 0, vcc
	v_cndmask_b32_e64 v49, v49, 0, vcc
	v_cndmask_b32_e64 v33, v33, 0, vcc
	v_mov_b32_dpp v102, v81 quad_perm:[1,0,3,2] row_mask:0xf bank_mask:0xf
	v_mov_b32_dpp v103, v65 quad_perm:[1,0,3,2] row_mask:0xf bank_mask:0xf
	v_mov_b32_dpp v104, v49 quad_perm:[1,0,3,2] row_mask:0xf bank_mask:0xf
	v_mov_b32_dpp v105, v33 quad_perm:[1,0,3,2] row_mask:0xf bank_mask:0xf
	s_and_saveexec_b64 s[22:23], s[8:9]
	v_cvt_pk_bf16_f32 v81, v81, v102
	v_cvt_pk_bf16_f32 v65, v65, v103
	v_cvt_pk_bf16_f32 v49, v49, v104
	v_cvt_pk_bf16_f32 v33, v33, v105
	global_store_dword v[98:99], v81, off
	global_store_dword v[98:99], v65, off offset:64
; __device__ __forceinline__ float bf2f(unsigned short b) { return __uint_as_float(((unsigned)b) << 16); }
; __device__ __forceinline__ int crow(int r, int hi) { return (r & 3) + 8 * (r >> 2) + 4 * hi; }
; __device__ __forceinline__ void phase_x3(const Args& a, unsigned char* ldsg, int G) {
;     ...
;         if (hi == 0) li_l[r32] = l_reg; asm volatile("s_waitcnt lgkmcnt(0)" ::: "memory");
; #pragma unroll
;         for (int r = 0; r < 16; ++r) { const int orow = crow(r, hi); const float rli = __builtin_amdgcn_rcpf(li_l[orow]); const int grow = R0 + wid * QBLK + orow; const size_t off = (size_t)grow * DM + hb;
; #pragma unroll
;             for (int d0 = 0; d0 < 4; ++d0) { float v = o[d0][r] * rli * bf2f(GBp[off + d0 * 32 + r32]); if (grow < ROW_META) v = 0.f;
;                 const float vn = __shfl_xor(v, 1);
;                 if ((r32 & 1) == 0) *(unsigned*)(OG + off + d0 * 32 + r32) = cvtpk(v, vn); } }
	global_store_dword v[98:99], v49, off offset:128
	global_store_dword v[98:99], v33, off offset:192
	s_or_b64 exec, exec, s[22:23]
	v_or_b32_e32 v96, 2, v188
	v_or_b32_e32 v96, s0, v96
	v_ashrrev_i32_e32 v97, 31, v96
	v_lshlrev_b64 v[98:99], 11, v[96:97]
	v_lshl_add_u64 v[98:99], v[98:99], 0, s[40:41]
	v_lshlrev_b64 v[98:99], 1, v[98:99]
	v_lshl_add_u64 v[98:99], v[166:167], 0, v[98:99]
	v_lshlrev_b32_e32 v8, 16, v8
	v_lshlrev_b32_e32 v9, 16, v9
	v_lshlrev_b32_e32 v10, 16, v10
	v_lshlrev_b32_e32 v11, 16, v11
	v_cmp_gt_i32_e32 vcc, s64, v96
	s_nop 0
	v_mul_f32_e32 v82, v82, v140
	v_mul_f32_e32 v66, v66, v140
	v_mul_f32_e32 v50, v50, v140
	v_mul_f32_e32 v34, v34, v140
	v_mul_f32_e32 v82, v82, v8
	v_mul_f32_e32 v66, v66, v9
	v_mul_f32_e32 v50, v50, v10
	v_mul_f32_e32 v34, v34, v11
	v_cndmask_b32_e64 v82, v82, 0, vcc
	v_cndmask_b32_e64 v66, v66, 0, vcc
	v_cndmask_b32_e64 v50, v50, 0, vcc
	v_cndmask_b32_e64 v34, v34, 0, vcc
	v_mov_b32_dpp v102, v82 quad_perm:[1,0,3,2] row_mask:0xf bank_mask:0xf
	v_mov_b32_dpp v103, v66 quad_perm:[1,0,3,2] row_mask:0xf bank_mask:0xf
	v_mov_b32_dpp v104, v50 quad_perm:[1,0,3,2] row_mask:0xf bank_mask:0xf
	v_mov_b32_dpp v105, v34 quad_perm:[1,0,3,2] row_mask:0xf bank_mask:0xf
	s_and_saveexec_b64 s[22:23], s[8:9]
	v_cvt_pk_bf16_f32 v82, v82, v102
	v_cvt_pk_bf16_f32 v66, v66, v103
	v_cvt_pk_bf16_f32 v50, v50, v104
	v_cvt_pk_bf16_f32 v34, v34, v105
	global_store_dword v[98:99], v82, off
	global_store_dword v[98:99], v66, off offset:64
	global_store_dword v[98:99], v50, off offset:128
	global_store_dword v[98:99], v34, off offset:192
	s_or_b64 exec, exec, s[22:23]
	v_or_b32_e32 v96, 3, v188
	v_or_b32_e32 v96, s0, v96
	v_ashrrev_i32_e32 v97, 31, v96
	v_lshlrev_b64 v[98:99], 11, v[96:97]
	v_lshl_add_u64 v[98:99], v[98:99], 0, s[40:41]
	v_lshlrev_b64 v[98:99], 1, v[98:99]
	v_lshl_add_u64 v[98:99], v[166:167], 0, v[98:99]
	v_lshlrev_b32_e32 v12, 16, v12
	v_lshlrev_b32_e32 v13, 16, v13
	v_lshlrev_b32_e32 v14, 16, v14
	v_lshlrev_b32_e32 v15, 16, v15
	v_cmp_gt_i32_e32 vcc, s64, v96
	s_nop 0
	v_mul_f32_e32 v83, v83, v141
	v_mul_f32_e32 v67, v67, v141
	v_mul_f32_e32 v51, v51, v141
	v_mul_f32_e32 v35, v35, v141
	v_mul_f32_e32 v83, v83, v12
	v_mul_f32_e32 v67, v67, v13
	v_mul_f32_e32 v51, v51, v14
	v_mul_f32_e32 v35, v35, v15
	v_cndmask_b32_e64 v83, v83, 0, vcc
	v_cndmask_b32_e64 v67, v67, 0, vcc
	v_cndmask_b32_e64 v51, v51, 0, vcc
	v_cndmask_b32_e64 v35, v35, 0, vcc
	v_mov_b32_dpp v102, v83 quad_perm:[1,0,3,2] row_mask:0xf bank_mask:0xf
	v_mov_b32_dpp v103, v67 quad_perm:[1,0,3,2] row_mask:0xf bank_mask:0xf
	v_mov_b32_dpp v104, v51 quad_perm:[1,0,3,2] row_mask:0xf bank_mask:0xf
	v_mov_b32_dpp v105, v35 quad_perm:[1,0,3,2] row_mask:0xf bank_mask:0xf
	s_and_saveexec_b64 s[22:23], s[8:9]
	v_cvt_pk_bf16_f32 v83, v83, v102
	v_cvt_pk_bf16_f32 v67, v67, v103
	v_cvt_pk_bf16_f32 v51, v51, v104
	v_cvt_pk_bf16_f32 v35, v35, v105
	global_store_dword v[98:99], v83, off
	global_store_dword v[98:99], v67, off offset:64
	global_store_dword v[98:99], v51, off offset:128
	global_store_dword v[98:99], v35, off offset:192
	s_or_b64 exec, exec, s[22:23]
	v_or_b32_e32 v96, 8, v188
	v_or_b32_e32 v96, s0, v96
	v_ashrrev_i32_e32 v97, 31, v96
	v_lshlrev_b64 v[98:99], 11, v[96:97]
	v_lshl_add_u64 v[98:99], v[98:99], 0, s[40:41]
	v_lshlrev_b64 v[98:99], 1, v[98:99]
	v_lshl_add_u64 v[98:99], v[166:167], 0, v[98:99]
	v_lshlrev_b32_e32 v16, 16, v16
	v_lshlrev_b32_e32 v17, 16, v17
	v_lshlrev_b32_e32 v18, 16, v18
	v_lshlrev_b32_e32 v19, 16, v19
	v_cmp_gt_i32_e32 vcc, s64, v96
	s_nop 0
	v_mul_f32_e32 v84, v84, v142
	v_mul_f32_e32 v68, v68, v142
	v_mul_f32_e32 v52, v52, v142
	v_mul_f32_e32 v36, v36, v142
	v_mul_f32_e32 v84, v84, v16
	v_mul_f32_e32 v68, v68, v17
	v_mul_f32_e32 v52, v52, v18
	v_mul_f32_e32 v36, v36, v19
	v_cndmask_b32_e64 v84, v84, 0, vcc
	v_cndmask_b32_e64 v68, v68, 0, vcc
	v_cndmask_b32_e64 v52, v52, 0, vcc
	v_cndmask_b32_e64 v36, v36, 0, vcc
	v_mov_b32_dpp v102, v84 quad_perm:[1,0,3,2] row_mask:0xf bank_mask:0xf
	v_mov_b32_dpp v103, v68 quad_perm:[1,0,3,2] row_mask:0xf bank_mask:0xf
	v_mov_b32_dpp v104, v52 quad_perm:[1,0,3,2] row_mask:0xf bank_mask:0xf
	v_mov_b32_dpp v105, v36 quad_perm:[1,0,3,2] row_mask:0xf bank_mask:0xf
	s_and_saveexec_b64 s[22:23], s[8:9]
	v_cvt_pk_bf16_f32 v84, v84, v102
	v_cvt_pk_bf16_f32 v68, v68, v103
	v_cvt_pk_bf16_f32 v52, v52, v104
	v_cvt_pk_bf16_f32 v36, v36, v105
	global_store_dword v[98:99], v84, off
	global_store_dword v[98:99], v68, off offset:64
	global_store_dword v[98:99], v52, off offset:128
	global_store_dword v[98:99], v36, off offset:192
	s_or_b64 exec, exec, s[22:23]
	v_or_b32_e32 v96, 9, v188
	v_or_b32_e32 v96, s0, v96
	v_ashrrev_i32_e32 v97, 31, v96
	v_lshlrev_b64 v[98:99], 11, v[96:97]
	v_lshl_add_u64 v[98:99], v[98:99], 0, s[40:41]
	v_lshlrev_b64 v[98:99], 1, v[98:99]
	v_lshl_add_u64 v[98:99], v[166:167], 0, v[98:99]
	v_lshlrev_b32_e32 v20, 16, v20
	v_lshlrev_b32_e32 v21, 16, v21
	v_lshlrev_b32_e32 v22, 16, v22
	v_lshlrev_b32_e32 v23, 16, v23
	v_cmp_gt_i32_e32 vcc, s64, v96
	s_nop 0
	v_mul_f32_e32 v85, v85, v143
	v_mul_f32_e32 v69, v69, v143
	v_mul_f32_e32 v53, v53, v143
	v_mul_f32_e32 v37, v37, v143
	v_mul_f32_e32 v85, v85, v20
	v_mul_f32_e32 v69, v69, v21
	v_mul_f32_e32 v53, v53, v22
	v_mul_f32_e32 v37, v37, v23
	v_cndmask_b32_e64 v85, v85, 0, vcc
	v_cndmask_b32_e64 v69, v69, 0, vcc
	v_cndmask_b32_e64 v53, v53, 0, vcc
	v_cndmask_b32_e64 v37, v37, 0, vcc
	v_mov_b32_dpp v102, v85 quad_perm:[1,0,3,2] row_mask:0xf bank_mask:0xf
	v_mov_b32_dpp v103, v69 quad_perm:[1,0,3,2] row_mask:0xf bank_mask:0xf
	v_mov_b32_dpp v104, v53 quad_perm:[1,0,3,2] row_mask:0xf bank_mask:0xf
; __device__ __forceinline__ float bf2f(unsigned short b) { return __uint_as_float(((unsigned)b) << 16); }
; __device__ __forceinline__ int crow(int r, int hi) { return (r & 3) + 8 * (r >> 2) + 4 * hi; }
; __device__ __forceinline__ void phase_x3(const Args& a, unsigned char* ldsg, int G) {
;     ...
;         if (hi == 0) li_l[r32] = l_reg; asm volatile("s_waitcnt lgkmcnt(0)" ::: "memory");
; #pragma unroll
;         for (int r = 0; r < 16; ++r) { const int orow = crow(r, hi); const float rli = __builtin_amdgcn_rcpf(li_l[orow]); const int grow = R0 + wid * QBLK + orow; const size_t off = (size_t)grow * DM + hb;
; #pragma unroll
;             for (int d0 = 0; d0 < 4; ++d0) { float v = o[d0][r] * rli * bf2f(GBp[off + d0 * 32 + r32]); if (grow < ROW_META) v = 0.f;
;                 const float vn = __shfl_xor(v, 1);
;                 if ((r32 & 1) == 0) *(unsigned*)(OG + off + d0 * 32 + r32) = cvtpk(v, vn); } }
	v_mov_b32_dpp v105, v37 quad_perm:[1,0,3,2] row_mask:0xf bank_mask:0xf
	s_and_saveexec_b64 s[22:23], s[8:9]
	v_cvt_pk_bf16_f32 v85, v85, v102
	v_cvt_pk_bf16_f32 v69, v69, v103
	v_cvt_pk_bf16_f32 v53, v53, v104
	v_cvt_pk_bf16_f32 v37, v37, v105
	global_store_dword v[98:99], v85, off
	global_store_dword v[98:99], v69, off offset:64
	global_store_dword v[98:99], v53, off offset:128
	global_store_dword v[98:99], v37, off offset:192
	s_or_b64 exec, exec, s[22:23]
	v_or_b32_e32 v96, 10, v188
	v_or_b32_e32 v96, s0, v96
	v_ashrrev_i32_e32 v97, 31, v96
	v_lshlrev_b64 v[98:99], 11, v[96:97]
	v_lshl_add_u64 v[98:99], v[98:99], 0, s[40:41]
	v_lshlrev_b64 v[98:99], 1, v[98:99]
	v_lshl_add_u64 v[98:99], v[166:167], 0, v[98:99]
	v_lshlrev_b32_e32 v24, 16, v24
	v_lshlrev_b32_e32 v25, 16, v25
	v_lshlrev_b32_e32 v26, 16, v26
	v_lshlrev_b32_e32 v27, 16, v27
	v_cmp_gt_i32_e32 vcc, s64, v96
	s_nop 0
	v_mul_f32_e32 v86, v86, v144
	v_mul_f32_e32 v70, v70, v144
	v_mul_f32_e32 v54, v54, v144
	v_mul_f32_e32 v38, v38, v144
	v_mul_f32_e32 v86, v86, v24
	v_mul_f32_e32 v70, v70, v25
	v_mul_f32_e32 v54, v54, v26
	v_mul_f32_e32 v38, v38, v27
	v_cndmask_b32_e64 v86, v86, 0, vcc
	v_cndmask_b32_e64 v70, v70, 0, vcc
	v_cndmask_b32_e64 v54, v54, 0, vcc
	v_cndmask_b32_e64 v38, v38, 0, vcc
	v_mov_b32_dpp v102, v86 quad_perm:[1,0,3,2] row_mask:0xf bank_mask:0xf
	v_mov_b32_dpp v103, v70 quad_perm:[1,0,3,2] row_mask:0xf bank_mask:0xf
	v_mov_b32_dpp v104, v54 quad_perm:[1,0,3,2] row_mask:0xf bank_mask:0xf
	v_mov_b32_dpp v105, v38 quad_perm:[1,0,3,2] row_mask:0xf bank_mask:0xf
	s_and_saveexec_b64 s[22:23], s[8:9]
	v_cvt_pk_bf16_f32 v86, v86, v102
	v_cvt_pk_bf16_f32 v70, v70, v103
	v_cvt_pk_bf16_f32 v54, v54, v104
	v_cvt_pk_bf16_f32 v38, v38, v105
	global_store_dword v[98:99], v86, off
	global_store_dword v[98:99], v70, off offset:64
	global_store_dword v[98:99], v54, off offset:128
	global_store_dword v[98:99], v38, off offset:192
	s_or_b64 exec, exec, s[22:23]
	v_or_b32_e32 v96, 11, v188
	v_or_b32_e32 v96, s0, v96
	v_ashrrev_i32_e32 v97, 31, v96
	v_lshlrev_b64 v[98:99], 11, v[96:97]
	v_lshl_add_u64 v[98:99], v[98:99], 0, s[40:41]
	v_lshlrev_b64 v[98:99], 1, v[98:99]
	v_lshl_add_u64 v[98:99], v[166:167], 0, v[98:99]
	v_lshlrev_b32_e32 v28, 16, v28
	v_lshlrev_b32_e32 v29, 16, v29
	v_lshlrev_b32_e32 v30, 16, v30
	v_lshlrev_b32_e32 v31, 16, v31
	v_cmp_gt_i32_e32 vcc, s64, v96
	s_nop 0
	v_mul_f32_e32 v87, v87, v145
	v_mul_f32_e32 v71, v71, v145
	v_mul_f32_e32 v55, v55, v145
	v_mul_f32_e32 v39, v39, v145
	v_mul_f32_e32 v87, v87, v28
	v_mul_f32_e32 v71, v71, v29
	v_mul_f32_e32 v55, v55, v30
	v_mul_f32_e32 v39, v39, v31
	v_cndmask_b32_e64 v87, v87, 0, vcc
	v_cndmask_b32_e64 v71, v71, 0, vcc
	v_cndmask_b32_e64 v55, v55, 0, vcc
	v_cndmask_b32_e64 v39, v39, 0, vcc
	v_mov_b32_dpp v102, v87 quad_perm:[1,0,3,2] row_mask:0xf bank_mask:0xf
	v_mov_b32_dpp v103, v71 quad_perm:[1,0,3,2] row_mask:0xf bank_mask:0xf
	v_mov_b32_dpp v104, v55 quad_perm:[1,0,3,2] row_mask:0xf bank_mask:0xf
	v_mov_b32_dpp v105, v39 quad_perm:[1,0,3,2] row_mask:0xf bank_mask:0xf
	s_and_saveexec_b64 s[22:23], s[8:9]
	v_cvt_pk_bf16_f32 v87, v87, v102
	v_cvt_pk_bf16_f32 v71, v71, v103
	v_cvt_pk_bf16_f32 v55, v55, v104
	v_cvt_pk_bf16_f32 v39, v39, v105
	global_store_dword v[98:99], v87, off
	global_store_dword v[98:99], v71, off offset:64
	global_store_dword v[98:99], v55, off offset:128
	global_store_dword v[98:99], v39, off offset:192
	s_or_b64 exec, exec, s[22:23]
	v_or_b32_e32 v96, 16, v188
	v_or_b32_e32 v96, s0, v96
	v_ashrrev_i32_e32 v97, 31, v96
	v_lshlrev_b64 v[98:99], 11, v[96:97]
	v_lshl_add_u64 v[98:99], v[98:99], 0, s[40:41]
	v_lshlrev_b64 v[98:99], 1, v[98:99]
	v_lshl_add_u64 v[98:99], v[166:167], 0, v[98:99]
	v_lshlrev_b32_e32 v106, 16, v106
	v_lshlrev_b32_e32 v107, 16, v107
	v_lshlrev_b32_e32 v108, 16, v108
	v_lshlrev_b32_e32 v109, 16, v109
	v_cmp_gt_i32_e32 vcc, s64, v96
	s_nop 0
	v_mul_f32_e32 v88, v88, v146
	v_mul_f32_e32 v72, v72, v146
	v_mul_f32_e32 v56, v56, v146
	v_mul_f32_e32 v40, v40, v146
	v_mul_f32_e32 v88, v88, v106
	v_mul_f32_e32 v72, v72, v107
	v_mul_f32_e32 v56, v56, v108
	v_mul_f32_e32 v40, v40, v109
	v_cndmask_b32_e64 v88, v88, 0, vcc
	v_cndmask_b32_e64 v72, v72, 0, vcc
	v_cndmask_b32_e64 v56, v56, 0, vcc
	v_cndmask_b32_e64 v40, v40, 0, vcc
	v_mov_b32_dpp v102, v88 quad_perm:[1,0,3,2] row_mask:0xf bank_mask:0xf
	v_mov_b32_dpp v103, v72 quad_perm:[1,0,3,2] row_mask:0xf bank_mask:0xf
	v_mov_b32_dpp v104, v56 quad_perm:[1,0,3,2] row_mask:0xf bank_mask:0xf
	v_mov_b32_dpp v105, v40 quad_perm:[1,0,3,2] row_mask:0xf bank_mask:0xf
	s_and_saveexec_b64 s[22:23], s[8:9]
	v_cvt_pk_bf16_f32 v88, v88, v102
	v_cvt_pk_bf16_f32 v72, v72, v103
	v_cvt_pk_bf16_f32 v56, v56, v104
	v_cvt_pk_bf16_f32 v40, v40, v105
	global_store_dword v[98:99], v88, off
	global_store_dword v[98:99], v72, off offset:64
	global_store_dword v[98:99], v56, off offset:128
	global_store_dword v[98:99], v40, off offset:192
	s_or_b64 exec, exec, s[22:23]
	v_or_b32_e32 v96, 17, v188
	v_or_b32_e32 v96, s0, v96
	v_ashrrev_i32_e32 v97, 31, v96
	v_lshlrev_b64 v[98:99], 11, v[96:97]
	v_lshl_add_u64 v[98:99], v[98:99], 0, s[40:41]
	v_lshlrev_b64 v[98:99], 1, v[98:99]
	v_lshl_add_u64 v[98:99], v[166:167], 0, v[98:99]
	v_lshlrev_b32_e32 v110, 16, v110
	v_lshlrev_b32_e32 v111, 16, v111
	v_lshlrev_b32_e32 v112, 16, v112
	v_lshlrev_b32_e32 v113, 16, v113
	v_cmp_gt_i32_e32 vcc, s64, v96
	s_nop 0
	v_mul_f32_e32 v89, v89, v147
	v_mul_f32_e32 v73, v73, v147
	v_mul_f32_e32 v57, v57, v147
	v_mul_f32_e32 v41, v41, v147
	v_mul_f32_e32 v89, v89, v110
	v_mul_f32_e32 v73, v73, v111
	v_mul_f32_e32 v57, v57, v112
	v_mul_f32_e32 v41, v41, v113
	v_cndmask_b32_e64 v89, v89, 0, vcc
; __device__ __forceinline__ float bf2f(unsigned short b) { return __uint_as_float(((unsigned)b) << 16); }
; __device__ __forceinline__ int crow(int r, int hi) { return (r & 3) + 8 * (r >> 2) + 4 * hi; }
; __device__ __forceinline__ void phase_x3(const Args& a, unsigned char* ldsg, int G) {
;     ...
;         if (hi == 0) li_l[r32] = l_reg; asm volatile("s_waitcnt lgkmcnt(0)" ::: "memory");
; #pragma unroll
;         for (int r = 0; r < 16; ++r) { const int orow = crow(r, hi); const float rli = __builtin_amdgcn_rcpf(li_l[orow]); const int grow = R0 + wid * QBLK + orow; const size_t off = (size_t)grow * DM + hb;
; #pragma unroll
;             for (int d0 = 0; d0 < 4; ++d0) { float v = o[d0][r] * rli * bf2f(GBp[off + d0 * 32 + r32]); if (grow < ROW_META) v = 0.f;
;                 const float vn = __shfl_xor(v, 1);
;                 if ((r32 & 1) == 0) *(unsigned*)(OG + off + d0 * 32 + r32) = cvtpk(v, vn); } }
	v_cndmask_b32_e64 v73, v73, 0, vcc
	v_cndmask_b32_e64 v57, v57, 0, vcc
	v_cndmask_b32_e64 v41, v41, 0, vcc
	v_mov_b32_dpp v102, v89 quad_perm:[1,0,3,2] row_mask:0xf bank_mask:0xf
	v_mov_b32_dpp v103, v73 quad_perm:[1,0,3,2] row_mask:0xf bank_mask:0xf
	v_mov_b32_dpp v104, v57 quad_perm:[1,0,3,2] row_mask:0xf bank_mask:0xf
	v_mov_b32_dpp v105, v41 quad_perm:[1,0,3,2] row_mask:0xf bank_mask:0xf
	s_and_saveexec_b64 s[22:23], s[8:9]
	v_cvt_pk_bf16_f32 v89, v89, v102
	v_cvt_pk_bf16_f32 v73, v73, v103
	v_cvt_pk_bf16_f32 v57, v57, v104
	v_cvt_pk_bf16_f32 v41, v41, v105
	global_store_dword v[98:99], v89, off
	global_store_dword v[98:99], v73, off offset:64
	global_store_dword v[98:99], v57, off offset:128
	global_store_dword v[98:99], v41, off offset:192
	s_or_b64 exec, exec, s[22:23]
	v_or_b32_e32 v96, 18, v188
	v_or_b32_e32 v96, s0, v96
	v_ashrrev_i32_e32 v97, 31, v96
	v_lshlrev_b64 v[98:99], 11, v[96:97]
	v_lshl_add_u64 v[98:99], v[98:99], 0, s[40:41]
	v_lshlrev_b64 v[98:99], 1, v[98:99]
	v_lshl_add_u64 v[98:99], v[166:167], 0, v[98:99]
	v_lshlrev_b32_e32 v114, 16, v114
	v_lshlrev_b32_e32 v115, 16, v115
	v_lshlrev_b32_e32 v116, 16, v116
	v_lshlrev_b32_e32 v117, 16, v117
	v_cmp_gt_i32_e32 vcc, s64, v96
	s_nop 0
	v_mul_f32_e32 v90, v90, v148
	v_mul_f32_e32 v74, v74, v148
	v_mul_f32_e32 v58, v58, v148
	v_mul_f32_e32 v42, v42, v148
	v_mul_f32_e32 v90, v90, v114
	v_mul_f32_e32 v74, v74, v115
	v_mul_f32_e32 v58, v58, v116
	v_mul_f32_e32 v42, v42, v117
	v_cndmask_b32_e64 v90, v90, 0, vcc
	v_cndmask_b32_e64 v74, v74, 0, vcc
	v_cndmask_b32_e64 v58, v58, 0, vcc
	v_cndmask_b32_e64 v42, v42, 0, vcc
	v_mov_b32_dpp v102, v90 quad_perm:[1,0,3,2] row_mask:0xf bank_mask:0xf
	v_mov_b32_dpp v103, v74 quad_perm:[1,0,3,2] row_mask:0xf bank_mask:0xf
	v_mov_b32_dpp v104, v58 quad_perm:[1,0,3,2] row_mask:0xf bank_mask:0xf
	v_mov_b32_dpp v105, v42 quad_perm:[1,0,3,2] row_mask:0xf bank_mask:0xf
	s_and_saveexec_b64 s[22:23], s[8:9]
	v_cvt_pk_bf16_f32 v90, v90, v102
	v_cvt_pk_bf16_f32 v74, v74, v103
	v_cvt_pk_bf16_f32 v58, v58, v104
	v_cvt_pk_bf16_f32 v42, v42, v105
	global_store_dword v[98:99], v90, off
	global_store_dword v[98:99], v74, off offset:64
	global_store_dword v[98:99], v58, off offset:128
	global_store_dword v[98:99], v42, off offset:192
	s_or_b64 exec, exec, s[22:23]
	v_or_b32_e32 v96, 19, v188
	v_or_b32_e32 v96, s0, v96
	v_ashrrev_i32_e32 v97, 31, v96
	v_lshlrev_b64 v[98:99], 11, v[96:97]
	v_lshl_add_u64 v[98:99], v[98:99], 0, s[40:41]
	v_lshlrev_b64 v[98:99], 1, v[98:99]
	v_lshl_add_u64 v[98:99], v[166:167], 0, v[98:99]
	v_lshlrev_b32_e32 v118, 16, v118
	v_lshlrev_b32_e32 v119, 16, v119
	v_lshlrev_b32_e32 v120, 16, v120
	v_lshlrev_b32_e32 v121, 16, v121
	v_cmp_gt_i32_e32 vcc, s64, v96
	s_nop 0
	v_mul_f32_e32 v91, v91, v149
	v_mul_f32_e32 v75, v75, v149
	v_mul_f32_e32 v59, v59, v149
	v_mul_f32_e32 v43, v43, v149
	v_mul_f32_e32 v91, v91, v118
	v_mul_f32_e32 v75, v75, v119
	v_mul_f32_e32 v59, v59, v120
	v_mul_f32_e32 v43, v43, v121
	v_cndmask_b32_e64 v91, v91, 0, vcc
	v_cndmask_b32_e64 v75, v75, 0, vcc
	v_cndmask_b32_e64 v59, v59, 0, vcc
	v_cndmask_b32_e64 v43, v43, 0, vcc
	v_mov_b32_dpp v102, v91 quad_perm:[1,0,3,2] row_mask:0xf bank_mask:0xf
	v_mov_b32_dpp v103, v75 quad_perm:[1,0,3,2] row_mask:0xf bank_mask:0xf
	v_mov_b32_dpp v104, v59 quad_perm:[1,0,3,2] row_mask:0xf bank_mask:0xf
	v_mov_b32_dpp v105, v43 quad_perm:[1,0,3,2] row_mask:0xf bank_mask:0xf
	s_and_saveexec_b64 s[22:23], s[8:9]
	v_cvt_pk_bf16_f32 v91, v91, v102
	v_cvt_pk_bf16_f32 v75, v75, v103
	v_cvt_pk_bf16_f32 v59, v59, v104
	v_cvt_pk_bf16_f32 v43, v43, v105
	global_store_dword v[98:99], v91, off
	global_store_dword v[98:99], v75, off offset:64
	global_store_dword v[98:99], v59, off offset:128
	global_store_dword v[98:99], v43, off offset:192
	s_or_b64 exec, exec, s[22:23]
	v_or_b32_e32 v96, 24, v188
	v_or_b32_e32 v96, s0, v96
	v_ashrrev_i32_e32 v97, 31, v96
	v_lshlrev_b64 v[98:99], 11, v[96:97]
	v_lshl_add_u64 v[98:99], v[98:99], 0, s[40:41]
	v_lshlrev_b64 v[98:99], 1, v[98:99]
	v_lshl_add_u64 v[98:99], v[166:167], 0, v[98:99]
	v_lshlrev_b32_e32 v122, 16, v122
	v_lshlrev_b32_e32 v123, 16, v123
	v_lshlrev_b32_e32 v124, 16, v124
	v_lshlrev_b32_e32 v125, 16, v125
	v_cmp_gt_i32_e32 vcc, s64, v96
	s_nop 0
	v_mul_f32_e32 v92, v92, v150
	v_mul_f32_e32 v76, v76, v150
	v_mul_f32_e32 v60, v60, v150
	v_mul_f32_e32 v44, v44, v150
	v_mul_f32_e32 v92, v92, v122
	v_mul_f32_e32 v76, v76, v123
	v_mul_f32_e32 v60, v60, v124
	v_mul_f32_e32 v44, v44, v125
	v_cndmask_b32_e64 v92, v92, 0, vcc
	v_cndmask_b32_e64 v76, v76, 0, vcc
	v_cndmask_b32_e64 v60, v60, 0, vcc
	v_cndmask_b32_e64 v44, v44, 0, vcc
	v_mov_b32_dpp v102, v92 quad_perm:[1,0,3,2] row_mask:0xf bank_mask:0xf
	v_mov_b32_dpp v103, v76 quad_perm:[1,0,3,2] row_mask:0xf bank_mask:0xf
	v_mov_b32_dpp v104, v60 quad_perm:[1,0,3,2] row_mask:0xf bank_mask:0xf
	v_mov_b32_dpp v105, v44 quad_perm:[1,0,3,2] row_mask:0xf bank_mask:0xf
; __device__ __forceinline__ float bf2f(unsigned short b) { return __uint_as_float(((unsigned)b) << 16); }
; __device__ __forceinline__ int crow(int r, int hi) { return (r & 3) + 8 * (r >> 2) + 4 * hi; }
; __device__ __forceinline__ void phase_x3(const Args& a, unsigned char* ldsg, int G) {
;     ...
;         if (hi == 0) li_l[r32] = l_reg; asm volatile("s_waitcnt lgkmcnt(0)" ::: "memory");
; #pragma unroll
;         for (int r = 0; r < 16; ++r) { const int orow = crow(r, hi); const float rli = __builtin_amdgcn_rcpf(li_l[orow]); const int grow = R0 + wid * QBLK + orow; const size_t off = (size_t)grow * DM + hb;
; #pragma unroll
;             for (int d0 = 0; d0 < 4; ++d0) { float v = o[d0][r] * rli * bf2f(GBp[off + d0 * 32 + r32]); if (grow < ROW_META) v = 0.f;
;                 const float vn = __shfl_xor(v, 1);
;                 if ((r32 & 1) == 0) *(unsigned*)(OG + off + d0 * 32 + r32) = cvtpk(v, vn); } }
	s_and_saveexec_b64 s[22:23], s[8:9]
	v_cvt_pk_bf16_f32 v92, v92, v102
	v_cvt_pk_bf16_f32 v76, v76, v103
	v_cvt_pk_bf16_f32 v60, v60, v104
	v_cvt_pk_bf16_f32 v44, v44, v105
	global_store_dword v[98:99], v92, off
	global_store_dword v[98:99], v76, off offset:64
	global_store_dword v[98:99], v60, off offset:128
	global_store_dword v[98:99], v44, off offset:192
	s_or_b64 exec, exec, s[22:23]
	v_or_b32_e32 v96, 25, v188
	v_or_b32_e32 v96, s0, v96
	v_ashrrev_i32_e32 v97, 31, v96
	v_lshlrev_b64 v[98:99], 11, v[96:97]
	v_lshl_add_u64 v[98:99], v[98:99], 0, s[40:41]
	v_lshlrev_b64 v[98:99], 1, v[98:99]
	v_lshl_add_u64 v[98:99], v[166:167], 0, v[98:99]
	v_lshlrev_b32_e32 v126, 16, v126
	v_lshlrev_b32_e32 v127, 16, v127
	v_lshlrev_b32_e32 v128, 16, v128
	v_lshlrev_b32_e32 v129, 16, v129
	v_cmp_gt_i32_e32 vcc, s64, v96
	s_nop 0
	v_mul_f32_e32 v93, v93, v151
	v_mul_f32_e32 v77, v77, v151
	v_mul_f32_e32 v61, v61, v151
	v_mul_f32_e32 v45, v45, v151
	v_mul_f32_e32 v93, v93, v126
	v_mul_f32_e32 v77, v77, v127
	v_mul_f32_e32 v61, v61, v128
	v_mul_f32_e32 v45, v45, v129
	v_cndmask_b32_e64 v93, v93, 0, vcc
	v_cndmask_b32_e64 v77, v77, 0, vcc
	v_cndmask_b32_e64 v61, v61, 0, vcc
	v_cndmask_b32_e64 v45, v45, 0, vcc
	v_mov_b32_dpp v102, v93 quad_perm:[1,0,3,2] row_mask:0xf bank_mask:0xf
	v_mov_b32_dpp v103, v77 quad_perm:[1,0,3,2] row_mask:0xf bank_mask:0xf
	v_mov_b32_dpp v104, v61 quad_perm:[1,0,3,2] row_mask:0xf bank_mask:0xf
	v_mov_b32_dpp v105, v45 quad_perm:[1,0,3,2] row_mask:0xf bank_mask:0xf
	s_and_saveexec_b64 s[22:23], s[8:9]
	v_cvt_pk_bf16_f32 v93, v93, v102
	v_cvt_pk_bf16_f32 v77, v77, v103
	v_cvt_pk_bf16_f32 v61, v61, v104
	v_cvt_pk_bf16_f32 v45, v45, v105
	global_store_dword v[98:99], v93, off
	global_store_dword v[98:99], v77, off offset:64
	global_store_dword v[98:99], v61, off offset:128
	global_store_dword v[98:99], v45, off offset:192
	s_or_b64 exec, exec, s[22:23]
	v_or_b32_e32 v96, 26, v188
	v_or_b32_e32 v96, s0, v96
	v_ashrrev_i32_e32 v97, 31, v96
	v_lshlrev_b64 v[98:99], 11, v[96:97]
	v_lshl_add_u64 v[98:99], v[98:99], 0, s[40:41]
	v_lshlrev_b64 v[98:99], 1, v[98:99]
	v_lshl_add_u64 v[98:99], v[166:167], 0, v[98:99]
	v_lshlrev_b32_e32 v130, 16, v130
	v_lshlrev_b32_e32 v131, 16, v131
	v_lshlrev_b32_e32 v132, 16, v132
	v_lshlrev_b32_e32 v133, 16, v133
	v_cmp_gt_i32_e32 vcc, s64, v96
	s_nop 0
	v_mul_f32_e32 v94, v94, v152
	v_mul_f32_e32 v78, v78, v152
	v_mul_f32_e32 v62, v62, v152
	v_mul_f32_e32 v46, v46, v152
	v_mul_f32_e32 v94, v94, v130
	v_mul_f32_e32 v78, v78, v131
	v_mul_f32_e32 v62, v62, v132
	v_mul_f32_e32 v46, v46, v133
	v_cndmask_b32_e64 v94, v94, 0, vcc
	v_cndmask_b32_e64 v78, v78, 0, vcc
	v_cndmask_b32_e64 v62, v62, 0, vcc
	v_cndmask_b32_e64 v46, v46, 0, vcc
	v_mov_b32_dpp v102, v94 quad_perm:[1,0,3,2] row_mask:0xf bank_mask:0xf
	v_mov_b32_dpp v103, v78 quad_perm:[1,0,3,2] row_mask:0xf bank_mask:0xf
	v_mov_b32_dpp v104, v62 quad_perm:[1,0,3,2] row_mask:0xf bank_mask:0xf
	v_mov_b32_dpp v105, v46 quad_perm:[1,0,3,2] row_mask:0xf bank_mask:0xf
	s_and_saveexec_b64 s[22:23], s[8:9]
	v_cvt_pk_bf16_f32 v94, v94, v102
	v_cvt_pk_bf16_f32 v78, v78, v103
	v_cvt_pk_bf16_f32 v62, v62, v104
	v_cvt_pk_bf16_f32 v46, v46, v105
	global_store_dword v[98:99], v94, off
	global_store_dword v[98:99], v78, off offset:64
	global_store_dword v[98:99], v62, off offset:128
	global_store_dword v[98:99], v46, off offset:192
	s_or_b64 exec, exec, s[22:23]
	v_or_b32_e32 v96, 27, v188
	v_or_b32_e32 v96, s0, v96
	v_ashrrev_i32_e32 v97, 31, v96
	v_lshlrev_b64 v[98:99], 11, v[96:97]
	v_lshl_add_u64 v[98:99], v[98:99], 0, s[40:41]
	v_lshlrev_b64 v[98:99], 1, v[98:99]
	v_lshl_add_u64 v[98:99], v[166:167], 0, v[98:99]
	v_lshlrev_b32_e32 v134, 16, v134
	v_lshlrev_b32_e32 v135, 16, v135
	v_lshlrev_b32_e32 v136, 16, v136
	v_lshlrev_b32_e32 v137, 16, v137
	v_cmp_gt_i32_e32 vcc, s64, v96
	s_nop 0
	v_mul_f32_e32 v95, v95, v153
	v_mul_f32_e32 v79, v79, v153
	v_mul_f32_e32 v63, v63, v153
	v_mul_f32_e32 v47, v47, v153
	v_mul_f32_e32 v95, v95, v134
	v_mul_f32_e32 v79, v79, v135
	v_mul_f32_e32 v63, v63, v136
	v_mul_f32_e32 v47, v47, v137
	v_cndmask_b32_e64 v95, v95, 0, vcc
	v_cndmask_b32_e64 v79, v79, 0, vcc
	v_cndmask_b32_e64 v63, v63, 0, vcc
	v_cndmask_b32_e64 v47, v47, 0, vcc
	v_mov_b32_dpp v102, v95 quad_perm:[1,0,3,2] row_mask:0xf bank_mask:0xf
	v_mov_b32_dpp v103, v79 quad_perm:[1,0,3,2] row_mask:0xf bank_mask:0xf
	v_mov_b32_dpp v104, v63 quad_perm:[1,0,3,2] row_mask:0xf bank_mask:0xf
	v_mov_b32_dpp v105, v47 quad_perm:[1,0,3,2] row_mask:0xf bank_mask:0xf
	s_and_saveexec_b64 s[22:23], s[8:9]
	v_cvt_pk_bf16_f32 v95, v95, v102
	v_cvt_pk_bf16_f32 v79, v79, v103
	v_cvt_pk_bf16_f32 v63, v63, v104
	v_cvt_pk_bf16_f32 v47, v47, v105
	global_store_dword v[98:99], v95, off
	global_store_dword v[98:99], v79, off offset:64
	global_store_dword v[98:99], v63, off offset:128
	global_store_dword v[98:99], v47, off offset:192
	s_or_b64 exec, exec, s[22:23]
	s_branch .LBB0_2193
